# rmsnorm row loops: wave-wide sum of squares via DPP adds within rows + v_readlane across rows instead of six ds_bpermute rounds each behind an lgkmcnt(0) wait
# speedup vs baseline: 1.0061x; 1.0023x over previous
; __device__ __forceinline__ void rms_row2_bf16(const float* xrow, size_t stride, const float* g, bf16_t* orow, int lane) {
;     const f32x4* xr0 = (const f32x4*)xrow + lane; const f32x4* xr1 = (const f32x4*)(xrow + stride) + lane; const f32x4* gr = (const f32x4*)g + lane;
;     f32x4 v0[4], v1[4]; float s0 = 0.f, s1 = 0.f;
; #pragma unroll
;     for (int j = 0; j < 4; ++j) { v0[j] = xr0[64 * j]; v1[j] = xr1[64 * j]; }
; #pragma unroll
;     for (int j = 0; j < 4; ++j) { s0 += (v0[j].x * v0[j].x + v0[j].y * v0[j].y) + (v0[j].z * v0[j].z + v0[j].w * v0[j].w); s1 += (v1[j].x * v1[j].x + v1[j].y * v1[j].y) + (v1[j].z * v1[j].z + v1[j].w * v1[j].w); }
.LBB0_45:
	global_load_dwordx4 v[24:27], v[16:17], off
	global_load_dwordx4 v[8:11], v[16:17], off offset:1024
	global_load_dwordx4 v[0:3], v[16:17], off offset:3072
	global_load_dwordx4 v[4:7], v[16:17], off offset:2048
	v_lshl_add_u64 v[44:45], v[16:17], 0, s[52:53]
	global_load_dwordx4 v[28:31], v[12:13], off
	global_load_dwordx4 v[32:35], v[44:45], off
	global_load_dwordx4 v[36:39], v[44:45], off offset:1024
	global_load_dwordx4 v[40:43], v[44:45], off offset:3072
	s_nop 0
	global_load_dwordx4 v[44:47], v[44:45], off offset:2048
	v_lshl_add_u64 v[48:49], v[14:15], 0, s[12:13]
	s_add_i32 s6, s6, s8
	v_lshl_add_u64 v[16:17], v[16:17], 0, s[10:11]
	s_cmp_lt_i32 s6, 0x8000
	s_waitcnt vmcnt(8)
	v_pk_mul_f32 v[50:51], v[26:27], v[26:27]
	v_pk_mul_f32 v[52:53], v[24:25], v[24:25]
	s_waitcnt vmcnt(7)
	v_pk_mul_f32 v[54:55], v[10:11], v[10:11]
	v_pk_mul_f32 v[56:57], v[8:9], v[8:9]
	s_waitcnt vmcnt(5)
	v_mul_f32_e32 v58, v5, v5
	v_mul_f32_e32 v60, v7, v7
	v_pk_mov_b32 v[62:63], v[52:53], v[50:51] op_sel:[1,0]
	v_mov_b32_e32 v53, v51
	s_waitcnt vmcnt(3)
	v_pk_mul_f32 v[50:51], v[34:35], v[34:35]
	v_pk_mul_f32 v[66:67], v[32:33], v[32:33]
	v_pk_mov_b32 v[68:69], v[56:57], v[54:55] op_sel:[1,0]
	v_mov_b32_e32 v57, v55
	s_waitcnt vmcnt(2)
	v_pk_mul_f32 v[54:55], v[38:39], v[38:39]
	v_pk_mul_f32 v[70:71], v[36:37], v[36:37]
	v_mul_f32_e32 v75, v2, v2
	v_mul_f32_e32 v76, v3, v3
	v_pk_fma_f32 v[58:59], v[4:5], v[4:5], v[58:59] op_sel_hi:[1,1,0]
	v_pk_fma_f32 v[60:61], v[6:7], v[6:7], v[60:61] op_sel_hi:[1,1,0]
	v_pk_add_f32 v[52:53], v[62:63], v[52:53]
	v_pk_mov_b32 v[62:63], v[66:67], v[50:51] op_sel:[1,0]
	v_mov_b32_e32 v67, v51
	v_pk_add_f32 v[50:51], v[68:69], v[56:57]
	v_pk_mov_b32 v[56:57], v[70:71], v[54:55] op_sel:[1,0]
	v_mov_b32_e32 v71, v55
	v_mul_f32_e32 v73, v0, v0
	s_waitcnt vmcnt(0)
; __device__ __forceinline__ unsigned cvt_pk_bf16(float lo, float hi) { f32x2_t v = {lo, hi}; bf2_t r = __builtin_convertvector(v, bf2_t); return __builtin_bit_cast(unsigned, r); }
; __device__ __forceinline__ float wave_sum(float v) {
; #pragma unroll
;     for (int o = 1; o < 64; o <<= 1) v += __shfl_xor(v, o);
;     return v;
; }
; __device__ __forceinline__ void rms_row2_bf16(const float* xrow, size_t stride, const float* g, bf16_t* orow, int lane) {
;     ...
;     const float r0 = rsqrtf(wave_sum(s0) * (1.f / 1024.f) + 1e-6f), r1 = rsqrtf(wave_sum(s1) * (1.f / 1024.f) + 1e-6f);
;     u32x2* o0 = (u32x2*)orow + lane; u32x2* o1 = (u32x2*)(orow + stride) + lane;
; #pragma unroll
;     for (int j = 0; j < 4; ++j) { const f32x4 gg = gr[64 * j]; u32x2 o; o.x = cvt_pk_bf16(v0[j].x * r0 * gg.x, v0[j].y * r0 * gg.y); o.y = cvt_pk_bf16(v0[j].z * r0 * gg.z, v0[j].w * r0 * gg.w); o0[64 * j] = o;
;         u32x2 q; q.x = cvt_pk_bf16(v1[j].x * r1 * gg.x, v1[j].y * r1 * gg.y); q.y = cvt_pk_bf16(v1[j].z * r1 * gg.z, v1[j].w * r1 * gg.w); o1[64 * j] = q; }
	v_mul_f32_e32 v64, v45, v45
	v_mul_f32_e32 v72, v47, v47
	v_mov_b32_e32 v59, v75
	v_mov_b32_e32 v61, v76
	v_pk_add_f32 v[62:63], v[62:63], v[66:67]
	v_pk_add_f32 v[56:57], v[56:57], v[70:71]
	v_mul_f32_e32 v74, v1, v1
	v_mul_f32_e32 v77, v40, v40
	v_mul_f32_e32 v78, v41, v41
	v_mul_f32_e32 v79, v42, v42
	v_mul_f32_e32 v80, v43, v43
	v_pk_fma_f32 v[54:55], v[44:45], v[44:45], v[64:65] op_sel_hi:[1,1,0]
	v_pk_fma_f32 v[68:69], v[46:47], v[46:47], v[72:73] op_sel_hi:[1,1,0]
	v_pk_add_f32 v[52:53], v[52:53], v[52:53] op_sel:[0,1] op_sel_hi:[1,0]
	v_pk_add_f32 v[50:51], v[50:51], v[50:51] op_sel:[0,1] op_sel_hi:[1,0]
	v_pk_add_f32 v[58:59], v[58:59], v[60:61]
	v_pk_add_f32 v[60:61], v[62:63], v[62:63] op_sel:[0,1] op_sel_hi:[1,0]
	v_pk_add_f32 v[56:57], v[56:57], v[56:57] op_sel:[0,1] op_sel_hi:[1,0]
	v_mov_b32_e32 v55, v79
	v_mov_b32_e32 v69, v80
	v_mov_b32_e32 v53, v73
	v_mov_b32_e32 v51, v74
	v_mov_b32_e32 v61, v77
	v_mov_b32_e32 v57, v78
	v_pk_add_f32 v[54:55], v[54:55], v[68:69]
	v_pk_add_f32 v[50:51], v[52:53], v[50:51]
	v_pk_add_f32 v[52:53], v[60:61], v[56:57]
	v_pk_add_f32 v[50:51], v[50:51], v[58:59]
	v_pk_add_f32 v[52:53], v[52:53], v[54:55]
	v_mov_b32_e32 v55, v50
	v_mov_b32_e32 v54, v52
	v_mov_b32_e32 v50, v53
	v_pk_add_f32 v[50:51], v[54:55], v[50:51]
	s_nop 1
	v_add_f32_dpp v50, v50, v50 quad_perm:[1,0,3,2] row_mask:0xf bank_mask:0xf
	v_add_f32_dpp v51, v51, v51 quad_perm:[1,0,3,2] row_mask:0xf bank_mask:0xf
	s_nop 0
	v_add_f32_dpp v50, v50, v50 quad_perm:[2,3,0,1] row_mask:0xf bank_mask:0xf
	v_add_f32_dpp v51, v51, v51 quad_perm:[2,3,0,1] row_mask:0xf bank_mask:0xf
	s_nop 0
	v_add_f32_dpp v50, v50, v50 row_half_mirror row_mask:0xf bank_mask:0xf
	v_add_f32_dpp v51, v51, v51 row_half_mirror row_mask:0xf bank_mask:0xf
	s_nop 0
	v_add_f32_dpp v50, v50, v50 row_mirror row_mask:0xf bank_mask:0xf
	v_add_f32_dpp v51, v51, v51 row_mirror row_mask:0xf bank_mask:0xf
	s_nop 0
	v_readlane_b32 s16, v50, 0
	v_readlane_b32 s17, v50, 16
	v_readlane_b32 s18, v50, 32
	v_readlane_b32 s19, v50, 48
	v_readlane_b32 s20, v51, 0
	v_readlane_b32 s21, v51, 16
	v_readlane_b32 s22, v51, 32
	v_readlane_b32 s23, v51, 48
	s_nop 1
	v_mov_b32_e32 v50, s16
	v_add_f32_e32 v50, s17, v50
	v_add_f32_e32 v50, s18, v50
	v_add_f32_e32 v50, s19, v50
	v_mov_b32_e32 v51, s20
	v_add_f32_e32 v51, s21, v51
	v_add_f32_e32 v51, s22, v51
	v_add_f32_e32 v51, s23, v51
	s_nop 0
	v_pk_fma_f32 v[50:51], v[50:51], s[14:15], v[238:239] op_sel_hi:[1,0,0]
	s_nop 0
	v_mul_f32_e32 v52, 0x4b800000, v51
	v_cmp_gt_f32_e64 s[4:5], s54, v51
	v_mul_f32_e32 v53, 0x4b800000, v50
	v_cmp_gt_f32_e32 vcc, s54, v50
	v_cndmask_b32_e64 v51, v51, v52, s[4:5]
	v_rsq_f32_e32 v51, v51
	v_cndmask_b32_e32 v50, v50, v53, vcc
	v_rsq_f32_e32 v52, v50
	v_mul_f32_e32 v50, 0x45800000, v51
	v_cndmask_b32_e64 v50, v51, v50, s[4:5]
	v_mul_f32_e32 v53, 0x45800000, v52
	v_cndmask_b32_e32 v52, v52, v53, vcc
	v_pk_mul_f32 v[24:25], v[24:25], v[50:51] op_sel_hi:[1,0]
	v_pk_mul_f32 v[26:27], v[26:27], v[50:51] op_sel_hi:[1,0]
	v_pk_mul_f32 v[32:33], v[32:33], v[52:53] op_sel_hi:[1,0]
	v_pk_mul_f32 v[34:35], v[34:35], v[52:53] op_sel_hi:[1,0]
	v_pk_mul_f32 v[24:25], v[28:29], v[24:25]
	v_pk_mul_f32 v[26:27], v[30:31], v[26:27]
	v_pk_mul_f32 v[28:29], v[28:29], v[32:33]
	v_pk_mul_f32 v[30:31], v[30:31], v[34:35]
	v_cvt_pk_bf16_f32 v24, v24, v25
	v_cvt_pk_bf16_f32 v25, v26, v27
	v_cvt_pk_bf16_f32 v26, v28, v29
	v_cvt_pk_bf16_f32 v27, v30, v31
	global_store_dwordx2 v[14:15], v[24:25], off
	global_store_dwordx2 v[48:49], v[26:27], off
	v_pk_mul_f32 v[8:9], v[8:9], v[50:51] op_sel_hi:[1,0]
	v_pk_mul_f32 v[10:11], v[10:11], v[50:51] op_sel_hi:[1,0]
	v_pk_mul_f32 v[28:29], v[36:37], v[52:53] op_sel_hi:[1,0]
	v_pk_mul_f32 v[30:31], v[38:39], v[52:53] op_sel_hi:[1,0]
	v_pk_mul_f32 v[4:5], v[4:5], v[50:51] op_sel_hi:[1,0]
	v_pk_mul_f32 v[6:7], v[6:7], v[50:51] op_sel_hi:[1,0]
	v_pk_mul_f32 v[0:1], v[0:1], v[50:51] op_sel_hi:[1,0]
	v_pk_mul_f32 v[2:3], v[2:3], v[50:51] op_sel_hi:[1,0]
	v_pk_mul_f32 v[8:9], v[112:113], v[8:9]
	v_pk_mul_f32 v[10:11], v[114:115], v[10:11]
	v_pk_mul_f32 v[24:25], v[112:113], v[28:29]
	v_pk_mul_f32 v[26:27], v[114:115], v[30:31]
	v_cvt_pk_bf16_f32 v8, v8, v9
	v_cvt_pk_bf16_f32 v9, v10, v11
	v_cvt_pk_bf16_f32 v10, v24, v25
	v_cvt_pk_bf16_f32 v11, v26, v27
	global_store_dwordx2 v[14:15], v[8:9], off offset:512
	global_store_dwordx2 v[48:49], v[10:11], off offset:512
	v_pk_mul_f32 v[24:25], v[44:45], v[52:53] op_sel_hi:[1,0]
	v_pk_mul_f32 v[26:27], v[46:47], v[52:53] op_sel_hi:[1,0]
	v_pk_mul_f32 v[4:5], v[4:5], v[116:117]
	v_pk_mul_f32 v[6:7], v[6:7], v[118:119]
	v_pk_mul_f32 v[8:9], v[116:117], v[24:25]
	v_pk_mul_f32 v[10:11], v[118:119], v[26:27]
	v_cvt_pk_bf16_f32 v4, v4, v5
	v_cvt_pk_bf16_f32 v5, v6, v7
	v_cvt_pk_bf16_f32 v6, v8, v9
	v_cvt_pk_bf16_f32 v7, v10, v11
	global_store_dwordx2 v[14:15], v[4:5], off offset:1024
	global_store_dwordx2 v[48:49], v[6:7], off offset:1024
	v_pk_mul_f32 v[8:9], v[40:41], v[52:53] op_sel_hi:[1,0]
	v_pk_mul_f32 v[10:11], v[42:43], v[52:53] op_sel_hi:[1,0]
	v_pk_mul_f32 v[0:1], v[0:1], v[120:121]
	v_pk_mul_f32 v[2:3], v[2:3], v[122:123]
	v_pk_mul_f32 v[4:5], v[8:9], v[120:121]
	v_pk_mul_f32 v[6:7], v[10:11], v[122:123]
	v_cvt_pk_bf16_f32 v0, v0, v1
	v_cvt_pk_bf16_f32 v1, v2, v3
	v_cvt_pk_bf16_f32 v2, v4, v5
	v_cvt_pk_bf16_f32 v3, v6, v7
	global_store_dwordx2 v[14:15], v[0:1], off offset:1536
	global_store_dwordx2 v[48:49], v[2:3], off offset:1536
	v_lshl_add_u64 v[14:15], v[14:15], 0, s[40:41]
	s_cbranch_scc1 .LBB0_45

; __device__ __forceinline__ void rms_row2_bf16(const float* xrow, size_t stride, const float* g, bf16_t* orow, int lane) {
;     const f32x4* xr0 = (const f32x4*)xrow + lane; const f32x4* xr1 = (const f32x4*)(xrow + stride) + lane; const f32x4* gr = (const f32x4*)g + lane;
;     f32x4 v0[4], v1[4]; float s0 = 0.f, s1 = 0.f;
; #pragma unroll
;     for (int j = 0; j < 4; ++j) { v0[j] = xr0[64 * j]; v1[j] = xr1[64 * j]; }
; #pragma unroll
;     for (int j = 0; j < 4; ++j) { s0 += (v0[j].x * v0[j].x + v0[j].y * v0[j].y) + (v0[j].z * v0[j].z + v0[j].w * v0[j].w); s1 += (v1[j].x * v1[j].x + v1[j].y * v1[j].y) + (v1[j].z * v1[j].z + v1[j].w * v1[j].w); }
.LBB0_1064:
	v_lshl_add_u64 v[0:1], v[40:41], 0, s[42:43]
	global_load_dwordx4 v[28:31], v[40:41], off
	global_load_dwordx4 v[24:27], v[0:1], off
	global_load_dwordx4 v[20:23], v[40:41], off offset:1024
	global_load_dwordx4 v[16:19], v[0:1], off offset:1024
	global_load_dwordx4 v[12:15], v[40:41], off offset:2048
	global_load_dwordx4 v[8:11], v[0:1], off offset:2048
	global_load_dwordx4 v[4:7], v[40:41], off offset:3072
	s_nop 0
	global_load_dwordx4 v[0:3], v[0:1], off offset:3072
	s_add_i32 s4, s4, s30
	v_lshl_add_u64 v[40:41], v[40:41], 0, s[38:39]
	s_cmpk_gt_i32 s4, 0x7fff
	s_waitcnt vmcnt(7)
	v_pk_mul_f32 v[32:33], v[30:31], v[30:31]
	v_pk_mul_f32 v[34:35], v[28:29], v[28:29]
	s_waitcnt vmcnt(1)
	v_mul_f32_e32 v42, v4, v4
	v_pk_mov_b32 v[46:47], v[34:35], v[32:33] op_sel:[1,0]
	v_mov_b32_e32 v35, v33
	v_pk_add_f32 v[32:33], v[46:47], v[34:35]
	v_pk_mul_f32 v[34:35], v[26:27], v[26:27]
	v_pk_mul_f32 v[46:47], v[24:25], v[24:25]
	v_mul_f32_e32 v44, v5, v5
	v_pk_mov_b32 v[52:53], v[46:47], v[34:35] op_sel:[1,0]
	v_mov_b32_e32 v47, v35
	v_pk_add_f32 v[34:35], v[52:53], v[46:47]
	v_pk_mul_f32 v[46:47], v[22:23], v[22:23]
	v_pk_mul_f32 v[52:53], v[20:21], v[20:21]
	v_pk_add_f32 v[32:33], v[32:33], v[32:33] op_sel:[0,1] op_sel_hi:[1,0]
	v_pk_mov_b32 v[54:55], v[52:53], v[46:47] op_sel:[1,0]
	v_mov_b32_e32 v53, v47
	v_pk_add_f32 v[46:47], v[54:55], v[52:53]
	v_pk_mul_f32 v[52:53], v[18:19], v[18:19]
	v_pk_mul_f32 v[54:55], v[16:17], v[16:17]
	v_pk_add_f32 v[46:47], v[46:47], v[46:47] op_sel:[0,1] op_sel_hi:[1,0]
	v_pk_mov_b32 v[56:57], v[54:55], v[52:53] op_sel:[1,0]
	v_mov_b32_e32 v55, v53
	v_mov_b32_e32 v33, v42
	v_mov_b32_e32 v47, v44
	v_mul_f32_e32 v42, v13, v13
	v_pk_add_f32 v[52:53], v[56:57], v[54:55]
	v_mul_f32_e32 v54, v6, v6
	v_pk_add_f32 v[32:33], v[32:33], v[46:47]
	v_pk_fma_f32 v[46:47], v[12:13], v[12:13], v[42:43] op_sel_hi:[1,1,0]
	v_mul_f32_e32 v42, v15, v15
	v_mul_f32_e32 v56, v7, v7
	v_mov_b32_e32 v47, v54
	v_pk_fma_f32 v[54:55], v[14:15], v[14:15], v[42:43] op_sel_hi:[1,1,0]
	s_waitcnt vmcnt(0)
; __device__ __forceinline__ unsigned cvt_pk_bf16(float lo, float hi) { f32x2_t v = {lo, hi}; bf2_t r = __builtin_convertvector(v, bf2_t); return __builtin_bit_cast(unsigned, r); }
; __device__ __forceinline__ float wave_sum(float v) {
; #pragma unroll
;     for (int o = 1; o < 64; o <<= 1) v += __shfl_xor(v, o);
;     return v;
; }
; __device__ __forceinline__ void rms_row2_bf16(const float* xrow, size_t stride, const float* g, bf16_t* orow, int lane) {
;     ...
;     const float r0 = rsqrtf(wave_sum(s0) * (1.f / 1024.f) + 1e-6f), r1 = rsqrtf(wave_sum(s1) * (1.f / 1024.f) + 1e-6f);
;     u32x2* o0 = (u32x2*)orow + lane; u32x2* o1 = (u32x2*)(orow + stride) + lane;
; #pragma unroll
;     for (int j = 0; j < 4; ++j) { const f32x4 gg = gr[64 * j]; u32x2 o; o.x = cvt_pk_bf16(v0[j].x * r0 * gg.x, v0[j].y * r0 * gg.y); o.y = cvt_pk_bf16(v0[j].z * r0 * gg.z, v0[j].w * r0 * gg.w); o0[64 * j] = o;
;         u32x2 q; q.x = cvt_pk_bf16(v1[j].x * r1 * gg.x, v1[j].y * r1 * gg.y); q.y = cvt_pk_bf16(v1[j].z * r1 * gg.z, v1[j].w * r1 * gg.w); o1[64 * j] = q; }
	v_mul_f32_e32 v42, v0, v0
	v_mov_b32_e32 v55, v56
	v_pk_add_f32 v[46:47], v[46:47], v[54:55]
	v_mul_f32_e32 v44, v1, v1
	v_pk_add_f32 v[32:33], v[32:33], v[46:47]
	v_pk_add_f32 v[34:35], v[34:35], v[34:35] op_sel:[0,1] op_sel_hi:[1,0]
	v_pk_add_f32 v[46:47], v[52:53], v[52:53] op_sel:[0,1] op_sel_hi:[1,0]
	v_mov_b32_e32 v35, v42
	v_mov_b32_e32 v47, v44
	v_mul_f32_e32 v42, v9, v9
	v_pk_add_f32 v[34:35], v[34:35], v[46:47]
	v_pk_fma_f32 v[46:47], v[8:9], v[8:9], v[42:43] op_sel_hi:[1,1,0]
	v_mul_f32_e32 v42, v11, v11
	v_mul_f32_e32 v54, v2, v2
	v_mul_f32_e32 v55, v3, v3
	v_pk_fma_f32 v[52:53], v[10:11], v[10:11], v[42:43] op_sel_hi:[1,1,0]
	v_mov_b32_e32 v47, v54
	v_mov_b32_e32 v53, v55
	v_pk_add_f32 v[46:47], v[46:47], v[52:53]
	s_nop 0
	v_pk_add_f32 v[34:35], v[34:35], v[46:47]
	v_mov_b32_e32 v47, v32
	v_mov_b32_e32 v46, v34
	v_mov_b32_e32 v32, v35
	v_pk_add_f32 v[32:33], v[46:47], v[32:33]
	v_lshl_add_u64 v[46:47], v[38:39], 0, s[44:45]
	s_nop 1
	v_add_f32_dpp v32, v32, v32 quad_perm:[1,0,3,2] row_mask:0xf bank_mask:0xf
	v_add_f32_dpp v33, v33, v33 quad_perm:[1,0,3,2] row_mask:0xf bank_mask:0xf
	s_nop 0
	v_add_f32_dpp v32, v32, v32 quad_perm:[2,3,0,1] row_mask:0xf bank_mask:0xf
	v_add_f32_dpp v33, v33, v33 quad_perm:[2,3,0,1] row_mask:0xf bank_mask:0xf
	s_nop 0
	v_add_f32_dpp v32, v32, v32 row_half_mirror row_mask:0xf bank_mask:0xf
	v_add_f32_dpp v33, v33, v33 row_half_mirror row_mask:0xf bank_mask:0xf
	s_nop 0
	v_add_f32_dpp v32, v32, v32 row_mirror row_mask:0xf bank_mask:0xf
	v_add_f32_dpp v33, v33, v33 row_mirror row_mask:0xf bank_mask:0xf
	s_nop 0
	v_readlane_b32 s5, v32, 0
	v_readlane_b32 s6, v32, 16
	v_readlane_b32 s7, v32, 32
	v_readlane_b32 s8, v32, 48
	v_readlane_b32 s9, v33, 0
	v_readlane_b32 s12, v33, 16
	v_readlane_b32 s13, v33, 32
	v_readlane_b32 s14, v33, 48
	s_nop 1
	v_mov_b32_e32 v32, s5
	v_add_f32_e32 v32, s6, v32
	v_add_f32_e32 v32, s7, v32
	v_add_f32_e32 v32, s8, v32
	v_mov_b32_e32 v33, s9
	v_add_f32_e32 v33, s12, v33
	v_add_f32_e32 v33, s13, v33
	v_add_f32_e32 v33, s14, v33
	s_nop 0
	v_pk_fma_f32 v[32:33], v[32:33], s[36:37], v[238:239] op_sel_hi:[1,0,0]
	s_nop 0
	v_mul_f32_e32 v34, 0x4b800000, v33
	v_cmp_gt_f32_e64 s[0:1], s54, v33
	v_cmp_gt_f32_e32 vcc, s54, v32
	s_nop 0
	v_cndmask_b32_e64 v33, v33, v34, s[0:1]
	v_rsq_f32_e32 v33, v33
	s_nop 0
	v_mul_f32_e32 v34, 0x45800000, v33
	v_cndmask_b32_e64 v44, v33, v34, s[0:1]
	v_mul_f32_e32 v33, 0x4b800000, v32
	v_cndmask_b32_e32 v32, v32, v33, vcc
	v_rsq_f32_e32 v32, v32
	v_pk_mul_f32 v[28:29], v[28:29], v[44:45] op_sel_hi:[1,0]
	v_pk_mul_f32 v[30:31], v[30:31], v[44:45] op_sel_hi:[1,0]
	v_pk_mul_f32 v[20:21], v[20:21], v[44:45] op_sel_hi:[1,0]
	v_mul_f32_e32 v33, 0x45800000, v32
	v_cndmask_b32_e32 v42, v32, v33, vcc
	v_pk_mul_f32 v[24:25], v[24:25], v[42:43] op_sel_hi:[1,0]
	v_pk_mul_f32 v[26:27], v[26:27], v[42:43] op_sel_hi:[1,0]
	v_pk_mul_f32 v[22:23], v[22:23], v[44:45] op_sel_hi:[1,0]
	v_pk_mul_f32 v[16:17], v[16:17], v[42:43] op_sel_hi:[1,0]
	v_pk_mul_f32 v[18:19], v[18:19], v[42:43] op_sel_hi:[1,0]
	v_pk_mul_f32 v[12:13], v[12:13], v[44:45] op_sel_hi:[1,0]
	v_pk_mul_f32 v[14:15], v[14:15], v[44:45] op_sel_hi:[1,0]
	v_pk_mul_f32 v[8:9], v[8:9], v[42:43] op_sel_hi:[1,0]
	v_pk_mul_f32 v[10:11], v[10:11], v[42:43] op_sel_hi:[1,0]
	v_pk_mul_f32 v[4:5], v[4:5], v[44:45] op_sel_hi:[1,0]
	v_pk_mul_f32 v[6:7], v[6:7], v[44:45] op_sel_hi:[1,0]
	v_pk_mul_f32 v[0:1], v[0:1], v[42:43] op_sel_hi:[1,0]
	v_pk_mul_f32 v[2:3], v[2:3], v[42:43] op_sel_hi:[1,0]
	v_pk_mul_f32 v[28:29], v[112:113], v[28:29]
	v_pk_mul_f32 v[30:31], v[114:115], v[30:31]
	v_pk_mul_f32 v[24:25], v[112:113], v[24:25]
	v_pk_mul_f32 v[26:27], v[114:115], v[26:27]
	v_cvt_pk_bf16_f32 v28, v28, v29
	v_cvt_pk_bf16_f32 v29, v30, v31
	v_cvt_pk_bf16_f32 v24, v24, v25
	v_cvt_pk_bf16_f32 v25, v26, v27
	global_store_dwordx2 v[38:39], v[28:29], off
	global_store_dwordx2 v[46:47], v[24:25], off
	v_pk_mul_f32 v[20:21], v[20:21], v[116:117]
	v_pk_mul_f32 v[22:23], v[22:23], v[118:119]
	v_pk_mul_f32 v[16:17], v[116:117], v[16:17]
	v_pk_mul_f32 v[18:19], v[118:119], v[18:19]
	v_cvt_pk_bf16_f32 v20, v20, v21
	v_cvt_pk_bf16_f32 v21, v22, v23
	v_cvt_pk_bf16_f32 v16, v16, v17
	v_cvt_pk_bf16_f32 v17, v18, v19
	global_store_dwordx2 v[38:39], v[20:21], off offset:512
	global_store_dwordx2 v[46:47], v[16:17], off offset:512
	v_pk_mul_f32 v[12:13], v[12:13], v[120:121]
	v_pk_mul_f32 v[14:15], v[14:15], v[122:123]
	v_pk_mul_f32 v[8:9], v[120:121], v[8:9]
	v_pk_mul_f32 v[10:11], v[122:123], v[10:11]
	v_cvt_pk_bf16_f32 v12, v12, v13
	v_cvt_pk_bf16_f32 v13, v14, v15
	v_cvt_pk_bf16_f32 v8, v8, v9
	v_cvt_pk_bf16_f32 v9, v10, v11
	global_store_dwordx2 v[38:39], v[12:13], off offset:1024
	global_store_dwordx2 v[46:47], v[8:9], off offset:1024
	v_pk_mul_f32 v[4:5], v[4:5], v[124:125]
	v_pk_mul_f32 v[6:7], v[6:7], v[126:127]
	v_cvt_pk_bf16_f32 v4, v4, v5
	v_cvt_pk_bf16_f32 v5, v6, v7
	v_pk_mul_f32 v[0:1], v[0:1], v[124:125]
	v_pk_mul_f32 v[2:3], v[2:3], v[126:127]
	global_store_dwordx2 v[38:39], v[4:5], off offset:1536
	v_cvt_pk_bf16_f32 v0, v0, v1
	v_cvt_pk_bf16_f32 v1, v2, v3
	v_lshl_add_u64 v[38:39], v[38:39], 0, s[40:41]
	global_store_dwordx2 v[46:47], v[0:1], off offset:1536
	s_cbranch_scc0 .LBB0_1064

; __device__ __forceinline__ void rms_row_f32(float* xrow, const float* g, int lane) {
;     f32x4* xr = (f32x4*)xrow + lane; const f32x4* gr = (const f32x4*)g + lane;
;     f32x4 v[4]; float s = 0.f;
; #pragma unroll
;     for (int j = 0; j < 4; ++j) { v[j] = xr[64 * j]; s += (v[j].x * v[j].x + v[j].y * v[j].y) + (v[j].z * v[j].z + v[j].w * v[j].w); }
;     const float r = rsqrtf(wave_sum(s) * (1.f / 1024.f) + 1e-6f);
; #pragma unroll
;     for (int j = 0; j < 4; ++j) { const f32x4 gg = gr[64 * j]; xr[64 * j] = v[j] * r * gg; }
.LBB0_1263:
	global_load_dwordx4 v[12:15], v[2:3], off offset:-3072
	global_load_dwordx4 v[16:19], v[2:3], off offset:-2048
	global_load_dwordx4 v[20:23], v[2:3], off
	global_load_dwordx4 v[24:27], v[2:3], off offset:-1024
	global_load_dwordx4 v[28:31], v[0:1], off
	s_add_i32 s0, s0, s6
	s_cmpk_gt_i32 s0, 0x7fff
	s_waitcnt vmcnt(4)
	v_pk_mul_f32 v[32:33], v[14:15], v[14:15]
	v_pk_mul_f32 v[34:35], v[12:13], v[12:13]
	s_waitcnt vmcnt(3)
	v_pk_mul_f32 v[36:37], v[18:19], v[18:19]
	v_pk_mul_f32 v[38:39], v[16:17], v[16:17]
	v_pk_mov_b32 v[44:45], v[34:35], v[32:33] op_sel:[1,0]
	v_mov_b32_e32 v35, v33
	v_pk_mov_b32 v[32:33], v[38:39], v[36:37] op_sel:[1,0]
	v_mov_b32_e32 v39, v37
	s_waitcnt vmcnt(2)
	v_mul_f32_e32 v43, v21, v21
	s_waitcnt vmcnt(1)
	v_mul_f32_e32 v40, v25, v25
	v_mul_f32_e32 v42, v27, v27
	v_pk_add_f32 v[34:35], v[44:45], v[34:35]
	v_pk_add_f32 v[32:33], v[32:33], v[38:39]
	v_mul_f32_e32 v11, v20, v20
	v_mul_f32_e32 v46, v22, v22
	v_mul_f32_e32 v47, v23, v23
	v_pk_fma_f32 v[36:37], v[24:25], v[24:25], v[40:41] op_sel_hi:[1,1,0]
	v_pk_fma_f32 v[40:41], v[26:27], v[26:27], v[42:43] op_sel_hi:[1,1,0]
	v_pk_add_f32 v[34:35], v[34:35], v[34:35] op_sel:[0,1] op_sel_hi:[1,0]
	v_pk_add_f32 v[32:33], v[32:33], v[32:33] op_sel:[0,1] op_sel_hi:[1,0]
	v_mov_b32_e32 v37, v46
	v_mov_b32_e32 v41, v47
	v_mov_b32_e32 v35, v11
	v_mov_b32_e32 v33, v43
	v_pk_add_f32 v[36:37], v[36:37], v[40:41]
	v_pk_add_f32 v[32:33], v[34:35], v[32:33]
	s_nop 0
	v_pk_add_f32 v[32:33], v[32:33], v[36:37]
	s_nop 0
	v_add_f32_e32 v11, v32, v33
	s_nop 1
	v_add_f32_dpp v11, v11, v11 quad_perm:[1,0,3,2] row_mask:0xf bank_mask:0xf
	s_nop 1
	v_add_f32_dpp v11, v11, v11 quad_perm:[2,3,0,1] row_mask:0xf bank_mask:0xf
	s_nop 1
	v_add_f32_dpp v11, v11, v11 row_half_mirror row_mask:0xf bank_mask:0xf
	s_nop 1
	v_add_f32_dpp v11, v11, v11 row_mirror row_mask:0xf bank_mask:0xf
	s_nop 1
	v_readlane_b32 s8, v11, 0
	v_readlane_b32 s9, v11, 16
	v_readlane_b32 s10, v11, 32
	v_readlane_b32 s11, v11, 48
	s_nop 1
	v_mov_b32_e32 v11, s8
	v_add_f32_e32 v11, s9, v11
	v_add_f32_e32 v11, s10, v11
	v_add_f32_e32 v11, s11, v11
	v_fmamk_f32 v11, v11, 0x3a800000, v10
	v_mul_f32_e32 v32, 0x4b800000, v11
	v_cmp_gt_f32_e32 vcc, s1, v11
	s_nop 1
	v_cndmask_b32_e32 v11, v11, v32, vcc
	v_rsq_f32_e32 v11, v11
	s_nop 0
	v_mul_f32_e32 v32, 0x45800000, v11
	v_cndmask_b32_e32 v32, v11, v32, vcc
	v_pk_mul_f32 v[12:13], v[12:13], v[32:33] op_sel_hi:[1,0]
	v_pk_mul_f32 v[14:15], v[14:15], v[32:33] op_sel_hi:[1,0]
	s_waitcnt vmcnt(0)
	v_pk_mul_f32 v[12:13], v[28:29], v[12:13]
	v_pk_mul_f32 v[14:15], v[30:31], v[14:15]
	global_store_dwordx4 v[2:3], v[12:15], off offset:-3072
	v_pk_mul_f32 v[18:19], v[18:19], v[32:33] op_sel_hi:[1,0]
	v_pk_mul_f32 v[16:17], v[16:17], v[32:33] op_sel_hi:[1,0]
	v_pk_mul_f32 v[14:15], v[114:115], v[18:19]
	v_pk_mul_f32 v[12:13], v[112:113], v[16:17]
	global_store_dwordx4 v[2:3], v[12:15], off offset:-2048
	v_pk_mul_f32 v[16:17], v[26:27], v[32:33] op_sel_hi:[1,0]
	v_pk_mul_f32 v[18:19], v[24:25], v[32:33] op_sel_hi:[1,0]
	v_pk_mul_f32 v[14:15], v[118:119], v[16:17]
	v_pk_mul_f32 v[12:13], v[116:117], v[18:19]
	global_store_dwordx4 v[2:3], v[12:15], off offset:-1024
	v_pk_mul_f32 v[16:17], v[22:23], v[32:33] op_sel_hi:[1,0]
	v_pk_mul_f32 v[18:19], v[20:21], v[32:33] op_sel_hi:[1,0]
	v_pk_mul_f32 v[14:15], v[122:123], v[16:17]
	v_pk_mul_f32 v[12:13], v[120:121], v[18:19]
	global_store_dwordx4 v[2:3], v[12:15], off
	v_lshl_add_u64 v[2:3], v[2:3], 0, s[52:53]
	s_cbranch_scc0 .LBB0_1263
